# v32 plus nt cache policy on the read-once f32 weight and p loads of the conversion phase
# speedup vs baseline: 1.0081x; 1.0077x over previous
; DI unsigned pk2(float lo, float hi) { f32x2_t v = {lo, hi}; bf16x2_t b = __builtin_convertvector(v, bf16x2_t); return __builtin_bit_cast(unsigned, b); }
; DI int tid_() { int t = threadIdx.x; asm volatile("" : "+v"(t)); return t; }
; DI void conv_tile(const ConvJob& J, int t, lptr lds) {
;     const int tid = tid_(); const int nkt = J.K / 64;
;     const int kt = t % nkt, nt = t / nkt; const int k0 = kt * 64, n0d = nt * 256, n0s = n0d + (n0d >= J.split ? 8 : 0);
; #pragma unroll
;     for (int it = 0; it < 8; ++it) { const int kr = it * 8 + (tid >> 6), nc = (tid & 63) * 4;
;         int scol = n0s + nc;
;         if (n0d >= J.rlo && n0d < J.rhi) { const int d = n0d + nc - J.rlo, jj = d & 63, chunk = jj >> 3; scol = J.rlo + (n0s - n0d) + (d & ~63) + ((jj & 4) ? 32 + 4 * chunk : 4 * chunk); }
;         const f32x4 v = *(const f32x4*)(J.W + (size_t)(k0 + kr) * J.ldn + scol);
;         const float rsc = J.rs ? J.rs[k0 + kr] : 1.f;
;         lst<f32x4>(lds, (kr * 260 + nc) * 4, v * rsc); }
;     __syncthreads();
;     { const int n = tid >> 1, kh = (tid & 1) * 32;
; #pragma unroll
;         for (int q = 0; q < 4; ++q) { float v[8];
;             for (int e = 0; e < 8; ++e) v[e] = lld<float>(lds, ((kh + 8 * q + e) * 260 + n) * 4);
;             u32x4 w; w.x = pk2(v[0], v[1]); w.y = pk2(v[2], v[3]); w.z = pk2(v[4], v[5]); w.w = pk2(v[6], v[7]);
;             *(u32x4*)(J.Wt + (size_t)(n0d + n) * J.K + k0 + kh + 8 * q) = w; } }
;     __syncthreads();
.LBB0_101:
	v_add_u32_e32 v0, 56, v10
	v_mad_i64_i32 v[6:7], s[38:39], s11, v0, 0
	v_lshl_add_u64 v[6:7], v[6:7], 2, s[20:21]
	v_ashrrev_i32_e32 v3, 31, v2
	v_lshl_add_u64 v[2:3], v[2:3], 2, v[6:7]
	global_load_dwordx4 v[10:13], v[2:3], off nt
	v_ashrrev_i32_e32 v0, 1, v8
	v_lshlrev_b32_e32 v2, 5, v8
	v_and_b32_e32 v5, 32, v2
	v_add_u32_e32 v2, s2, v0
	s_movk_i32 s2, 0x104
	v_ashrrev_i32_e32 v3, 31, v2
	v_mad_u32_u24 v6, v5, s2, v0
	v_readlane_b32 s2, v250, 43
	s_sub_i32 s38, s55, s57
	v_lshlrev_b64 v[2:3], 11, v[2:3]
	v_readlane_b32 s3, v250, 44
	s_ashr_i32 s39, s38, 31
	v_lshlrev_b32_e32 v0, 1, v5
	v_lshl_add_u64 v[2:3], s[2:3], 0, v[2:3]
	v_lshl_add_u32 v5, v6, 2, 0
	v_lshl_add_u64 v[2:3], s[38:39], 1, v[2:3]
	v_lshl_add_u64 v[18:19], v[2:3], 0, v[0:1]
	s_waitcnt vmcnt(0)
	ds_write_b128 v124, v[96:99]
	ds_write_b128 v125, v[100:103]
	ds_write_b128 v126, v[104:107]
	ds_write_b128 v127, v[108:111]
	ds_write_b128 v128, v[112:115]
	ds_write_b128 v129, v[116:119]
	ds_write_b128 v130, v[120:123]
	ds_write_b128 v4, v[10:13] offset:8320
	s_waitcnt lgkmcnt(0)
	s_barrier
	ds_read_b32 v0, v5
	ds_read_b32 v2, v5 offset:1040
	ds_read_b32 v3, v5 offset:2080
	ds_read_b32 v4, v5 offset:3120
	ds_read_b32 v6, v5 offset:4160
	ds_read_b32 v7, v5 offset:5200
	ds_read_b32 v8, v5 offset:6240
	ds_read_b32 v9, v5 offset:7280
	ds_read_b32 v10, v5 offset:8320
	ds_read_b32 v11, v5 offset:9360
	ds_read_b32 v12, v5 offset:10400
	ds_read_b32 v13, v5 offset:11440
	ds_read_b32 v14, v5 offset:12480
	ds_read_b32 v15, v5 offset:13520
	ds_read_b32 v16, v5 offset:14560
	ds_read_b32 v17, v5 offset:15600
	ds_read_b32 v20, v5 offset:16640
	ds_read_b32 v21, v5 offset:17680
	ds_read_b32 v22, v5 offset:18720
	ds_read_b32 v23, v5 offset:19760
	ds_read_b32 v24, v5 offset:20800
	ds_read_b32 v25, v5 offset:21840
	ds_read_b32 v26, v5 offset:22880
	ds_read_b32 v27, v5 offset:23920
	ds_read_b32 v28, v5 offset:24960
	ds_read_b32 v29, v5 offset:26000
	ds_read_b32 v30, v5 offset:27040
	ds_read_b32 v31, v5 offset:28080
	ds_read_b32 v32, v5 offset:29120
	ds_read_b32 v33, v5 offset:30160
	ds_read_b32 v34, v5 offset:31200
	ds_read_b32 v35, v5 offset:32240
	s_waitcnt lgkmcnt(14)
	v_cvt_pk_bf16_f32 v2, v0, v2
	v_cvt_pk_bf16_f32 v3, v3, v4
	v_cvt_pk_bf16_f32 v4, v6, v7
	v_cvt_pk_bf16_f32 v5, v8, v9
	v_cvt_pk_bf16_f32 v6, v10, v11
	v_cvt_pk_bf16_f32 v7, v12, v13
	v_cvt_pk_bf16_f32 v8, v14, v15
	v_cvt_pk_bf16_f32 v9, v16, v17
	v_cvt_pk_bf16_f32 v10, v20, v21
	s_waitcnt lgkmcnt(12)
	v_cvt_pk_bf16_f32 v11, v22, v23
	s_waitcnt lgkmcnt(10)
	v_cvt_pk_bf16_f32 v12, v24, v25
	s_waitcnt lgkmcnt(8)
	v_cvt_pk_bf16_f32 v13, v26, v27
	s_waitcnt lgkmcnt(6)
	v_cvt_pk_bf16_f32 v14, v28, v29
	s_waitcnt lgkmcnt(4)
	v_cvt_pk_bf16_f32 v15, v30, v31
	s_waitcnt lgkmcnt(2)
	v_cvt_pk_bf16_f32 v16, v32, v33
	s_waitcnt lgkmcnt(0)
	v_cvt_pk_bf16_f32 v17, v34, v35
	global_store_dwordx4 v[18:19], v[2:5], off
	global_store_dwordx4 v[18:19], v[6:9], off offset:16
	global_store_dwordx4 v[18:19], v[10:13], off offset:32
	global_store_dwordx4 v[18:19], v[14:17], off offset:48
	s_barrier

; DI void conv_tile(const ConvJob& J, int t, lptr lds) {
;     const int tid = tid_(); const int nkt = J.K / 64;
;     const int kt = t % nkt, nt = t / nkt; const int k0 = kt * 64, n0d = nt * 256, n0s = n0d + (n0d >= J.split ? 8 : 0);
; #pragma unroll
;     for (int it = 0; it < 8; ++it) { const int kr = it * 8 + (tid >> 6), nc = (tid & 63) * 4;
;         int scol = n0s + nc;
;         if (n0d >= J.rlo && n0d < J.rhi) { const int d = n0d + nc - J.rlo, jj = d & 63, chunk = jj >> 3; scol = J.rlo + (n0s - n0d) + (d & ~63) + ((jj & 4) ? 32 + 4 * chunk : 4 * chunk); }
;         const f32x4 v = *(const f32x4*)(J.W + (size_t)(k0 + kr) * J.ldn + scol);
;         const float rsc = J.rs ? J.rs[k0 + kr] : 1.f;
;         lst<f32x4>(lds, (kr * 260 + nc) * 4, v * rsc); }
;     __syncthreads();
;     { const int n = tid >> 1, kh = (tid & 1) * 32;
; #pragma unroll
;         for (int q = 0; q < 4; ++q) { float v[8];
;             for (int e = 0; e < 8; ++e) v[e] = lld<float>(lds, ((kh + 8 * q + e) * 260 + n) * 4);
;             u32x4 w; w.x = pk2(v[0], v[1]); w.y = pk2(v[2], v[3]); w.z = pk2(v[4], v[5]); w.w = pk2(v[6], v[7]);
;             *(u32x4*)(J.Wt + (size_t)(n0d + n) * J.K + k0 + kh + 8 * q) = w; } }
; __global__ void __launch_bounds__(512) mega(Params p) {
;     ...
;             for (int g = bid_(); g < c6; g += gridDim.x) {
;                 ConvJob J;
;                 if (g < c1)      { J = ConvJob{Win, Wt_in, nullptr, 1024, ldw, NIN, even ? 2048 : (1 << 30), even ? 2048 : 0, even ? 3072 : 0}; conv_tile(J, g, lds); }
;                 else if (g < c2) { J = ConvJob{(even ? p.in[16] : p.in[19]) + (size_t)j * 1024 * 1024, Wt_out, nullptr, 1024, 1024, 1024, 1 << 30, 0, 0}; conv_tile(J, g - c1, lds); }
;                 else if (g < c3) { J = ConvJob{p.in[20] + (size_t)L * 1024 * 4096, Wt_up, p.in[4] + L * 1024, 1024, 4096, 4096, 1 << 30, 0, 0}; conv_tile(J, g - c2, lds); }
;                 else if (g < c4) { J = ConvJob{p.in[21] + (size_t)L * 4096 * 1024, Wt_down, nullptr, 4096, 1024, 1024, 1 << 30, 0, 0}; conv_tile(J, g - c3, lds); }
;                 else if (g < c5) { J = ConvJob{p.in[22] + (size_t)L * 256 * 1024, Wt_ple, nullptr, 256, 1024, 1024, 1 << 30, 0, 0}; conv_tile(J, g - c4, lds); }
;                 else             { J = ConvJob{p.in[23] + (size_t)L * 1024 * 1024, Wt_gate, nullptr, 1024, 1024, 1024, 1 << 30, 0, 0}; conv_tile(J, g - c5, lds); }
.LBB0_103:
	s_cmp_ge_i32 s56, s12
	s_mov_b64 s[2:3], -1
	s_cbranch_scc0 .LBB0_137
	s_cmp_ge_i32 s56, s17
	s_cbranch_scc0 .LBB0_134
	s_cmp_ge_i32 s56, s18
	s_cbranch_scc0 .LBB0_115
	s_cmp_ge_i32 s56, s19
	s_cbranch_scc0 .LBB0_112
	s_cmp_ge_i32 s56, s26
	s_cbranch_scc0 .LBB0_109
	s_add_i32 s2, s50, s56
	v_mov_b32_e32 v34, v194
	s_addk_i32 s2, 0xfdb0
	s_and_b32 s38, s55, 0x3c0
	s_and_b32 s3, s51, 0x7fffff00
	v_lshlrev_b32_e32 v0, 2, v34
	s_cmp_lt_u32 s2, 0x4000000
	v_ashrrev_i32_e32 v35, 6, v34
	v_and_b32_e32 v0, 0xfc, v0
	s_cselect_b32 s2, 0, 8
	v_or_b32_e32 v2, s3, v0
	v_add_u32_e32 v26, s38, v35
	v_add_u32_e32 v2, s2, v2
	v_ashrrev_i32_e32 v27, 31, v26
	v_lshlrev_b64 v[4:5], 12, v[26:27]
	v_ashrrev_i32_e32 v3, 31, v2
	v_lshl_add_u64 v[4:5], s[0:1], 0, v[4:5]
	v_lshlrev_b64 v[28:29], 2, v[2:3]
	v_lshl_add_u64 v[2:3], v[4:5], 0, v[28:29]
	v_add_u32_e32 v4, 8, v26
	v_add_u32_e32 v10, 16, v26
	v_add_u32_e32 v12, 24, v26
	v_add_u32_e32 v18, 32, v26
	v_add_u32_e32 v20, 40, v26
	v_add_u32_e32 v30, 48, v26
	v_add_u32_e32 v26, 56, v26
	v_ashrrev_i32_e32 v5, 31, v4
	v_ashrrev_i32_e32 v11, 31, v10
	v_ashrrev_i32_e32 v13, 31, v12
	v_ashrrev_i32_e32 v19, 31, v18
	v_ashrrev_i32_e32 v21, 31, v20
	v_ashrrev_i32_e32 v31, 31, v30
	v_ashrrev_i32_e32 v27, 31, v26
	v_lshlrev_b64 v[4:5], 12, v[4:5]
	v_lshlrev_b64 v[10:11], 12, v[10:11]
	v_lshlrev_b64 v[12:13], 12, v[12:13]
	v_lshlrev_b64 v[18:19], 12, v[18:19]
	v_lshlrev_b64 v[20:21], 12, v[20:21]
	v_lshlrev_b64 v[30:31], 12, v[30:31]
	v_lshlrev_b64 v[26:27], 12, v[26:27]
	v_lshl_add_u64 v[4:5], s[0:1], 0, v[4:5]
	v_lshl_add_u64 v[10:11], s[0:1], 0, v[10:11]
	v_lshl_add_u64 v[12:13], s[0:1], 0, v[12:13]
	v_lshl_add_u64 v[18:19], s[0:1], 0, v[18:19]
	v_lshl_add_u64 v[20:21], s[0:1], 0, v[20:21]
	v_lshl_add_u64 v[30:31], s[0:1], 0, v[30:31]
	v_lshl_add_u64 v[26:27], s[0:1], 0, v[26:27]
	v_lshl_add_u64 v[6:7], v[4:5], 0, v[28:29]
	v_lshl_add_u64 v[10:11], v[10:11], 0, v[28:29]
	v_lshl_add_u64 v[14:15], v[12:13], 0, v[28:29]
	v_lshl_add_u64 v[18:19], v[18:19], 0, v[28:29]
	v_lshl_add_u64 v[22:23], v[20:21], 0, v[28:29]
	v_lshl_add_u64 v[30:31], v[30:31], 0, v[28:29]
	v_lshl_add_u64 v[32:33], v[26:27], 0, v[28:29]
	global_load_dwordx4 v[2:5], v[2:3], off nt
	s_nop 0
	global_load_dwordx4 v[6:9], v[6:7], off nt
	s_nop 0
	global_load_dwordx4 v[10:13], v[10:11], off nt
	s_nop 0
	global_load_dwordx4 v[14:17], v[14:15], off nt
	s_nop 0
	global_load_dwordx4 v[18:21], v[18:19], off nt
	s_nop 0
	global_load_dwordx4 v[22:25], v[22:23], off nt
	s_nop 0
	global_load_dwordx4 v[26:29], v[30:31], off nt
	s_nop 0
	global_load_dwordx4 v[30:33], v[32:33], off nt
	v_ashrrev_i32_e32 v38, 1, v34
	v_lshlrev_b32_e32 v34, 5, v34
	v_and_b32_e32 v39, 32, v34
	s_movk_i32 s36, 0x104
	v_add_u32_e32 v34, s3, v38
	v_mad_u64_u32 v[36:37], s[2:3], v35, s36, v[0:1]
	v_mad_u32_u24 v0, v39, s36, v38
	v_lshl_add_u32 v35, v36, 2, 0
	v_lshl_add_u32 v36, v0, 2, 0
	v_readlane_b32 s2, v250, 53
	v_readlane_b32 s3, v250, 54
	s_lshl_b32 s82, s38, 1
	s_waitcnt vmcnt(7)
	ds_write_b128 v35, v[2:5]
	s_waitcnt vmcnt(6)
	ds_write_b128 v35, v[6:9] offset:8320
	s_waitcnt vmcnt(5)
	ds_write_b128 v35, v[10:13] offset:16640
	s_waitcnt vmcnt(4)
	ds_write_b128 v35, v[14:17] offset:24960
	s_waitcnt vmcnt(3)
	ds_write_b128 v35, v[18:21] offset:33280
	s_waitcnt vmcnt(2)
	ds_write_b128 v35, v[22:25] offset:41600
	s_waitcnt vmcnt(1)
	ds_write_b128 v35, v[26:29] offset:49920
	s_waitcnt vmcnt(0)
	ds_write_b128 v35, v[30:33] offset:58240
	s_waitcnt lgkmcnt(0)
	s_barrier
	ds_read_b32 v0, v36
	ds_read_b32 v2, v36 offset:1040
	ds_read_b32 v3, v36 offset:2080
	ds_read_b32 v4, v36 offset:3120
	ds_read_b32 v5, v36 offset:4160
	ds_read_b32 v6, v36 offset:5200
	ds_read_b32 v7, v36 offset:6240
	ds_read_b32 v8, v36 offset:7280
	v_ashrrev_i32_e32 v35, 31, v34
	s_waitcnt lgkmcnt(4)
	v_cvt_pk_bf16_f32 v3, v3, v4
	s_waitcnt lgkmcnt(2)
	v_cvt_pk_bf16_f32 v4, v5, v6
	v_cvt_pk_bf16_f32 v2, v0, v2
	s_waitcnt lgkmcnt(0)
	v_cvt_pk_bf16_f32 v5, v7, v8
	v_lshlrev_b64 v[6:7], 11, v[34:35]
	v_lshl_add_u64 v[6:7], s[2:3], 0, v[6:7]
	v_lshl_add_u64 v[6:7], v[6:7], 0, s[82:83]
	v_lshlrev_b32_e32 v0, 1, v39
	v_lshl_add_u64 v[6:7], v[6:7], 0, v[0:1]
	ds_read_b32 v0, v36 offset:8320
	ds_read_b32 v8, v36 offset:9360
	ds_read_b32 v9, v36 offset:10400
	ds_read_b32 v10, v36 offset:11440
	ds_read_b32 v11, v36 offset:12480
	ds_read_b32 v12, v36 offset:13520
	ds_read_b32 v13, v36 offset:14560
	ds_read_b32 v14, v36 offset:15600
	global_store_dwordx4 v[6:7], v[2:5], off
	s_mov_b64 s[2:3], 0
	s_waitcnt lgkmcnt(6)
	v_cvt_pk_bf16_f32 v2, v0, v8
	s_waitcnt lgkmcnt(4)
	v_cvt_pk_bf16_f32 v3, v9, v10
	s_waitcnt lgkmcnt(2)
	v_cvt_pk_bf16_f32 v4, v11, v12
	s_waitcnt lgkmcnt(0)
	v_cvt_pk_bf16_f32 v5, v13, v14
	ds_read_b32 v0, v36 offset:16640
	ds_read_b32 v8, v36 offset:17680
	ds_read_b32 v9, v36 offset:18720
	ds_read_b32 v10, v36 offset:19760
	ds_read_b32 v11, v36 offset:20800
	ds_read_b32 v12, v36 offset:21840
	ds_read_b32 v13, v36 offset:22880
	ds_read_b32 v14, v36 offset:23920
	global_store_dwordx4 v[6:7], v[2:5], off offset:16
	s_waitcnt lgkmcnt(6)
	s_nop 0
	v_cvt_pk_bf16_f32 v2, v0, v8
	s_waitcnt lgkmcnt(4)
	v_cvt_pk_bf16_f32 v3, v9, v10
	s_waitcnt lgkmcnt(2)
	v_cvt_pk_bf16_f32 v4, v11, v12
	s_waitcnt lgkmcnt(0)
	v_cvt_pk_bf16_f32 v5, v13, v14
	ds_read_b32 v0, v36 offset:24960
	ds_read_b32 v8, v36 offset:26000
	ds_read_b32 v9, v36 offset:27040
	ds_read_b32 v10, v36 offset:28080
	ds_read_b32 v11, v36 offset:29120
	ds_read_b32 v12, v36 offset:30160
	ds_read_b32 v13, v36 offset:31200
	ds_read_b32 v14, v36 offset:32240
	global_store_dwordx4 v[6:7], v[2:5], off offset:32
	s_waitcnt lgkmcnt(6)
	s_nop 0
	v_cvt_pk_bf16_f32 v2, v0, v8
	s_waitcnt lgkmcnt(4)
	v_cvt_pk_bf16_f32 v3, v9, v10
	s_waitcnt lgkmcnt(2)
	v_cvt_pk_bf16_f32 v4, v11, v12
	s_waitcnt lgkmcnt(0)
	v_cvt_pk_bf16_f32 v5, v13, v14
	global_store_dwordx4 v[6:7], v[2:5], off offset:48
	s_barrier
; DI void conv_tile(const ConvJob& J, int t, lptr lds) {
;     const int tid = tid_(); const int nkt = J.K / 64;
;     const int kt = t % nkt, nt = t / nkt; const int k0 = kt * 64, n0d = nt * 256, n0s = n0d + (n0d >= J.split ? 8 : 0);
; #pragma unroll
;     for (int it = 0; it < 8; ++it) { const int kr = it * 8 + (tid >> 6), nc = (tid & 63) * 4;
;         int scol = n0s + nc;
;         if (n0d >= J.rlo && n0d < J.rhi) { const int d = n0d + nc - J.rlo, jj = d & 63, chunk = jj >> 3; scol = J.rlo + (n0s - n0d) + (d & ~63) + ((jj & 4) ? 32 + 4 * chunk : 4 * chunk); }
;         const f32x4 v = *(const f32x4*)(J.W + (size_t)(k0 + kr) * J.ldn + scol);
;         const float rsc = J.rs ? J.rs[k0 + kr] : 1.f;
;         lst<f32x4>(lds, (kr * 260 + nc) * 4, v * rsc); }
;     __syncthreads();
;     { const int n = tid >> 1, kh = (tid & 1) * 32;
; #pragma unroll
;         for (int q = 0; q < 4; ++q) { float v[8];
;             for (int e = 0; e < 8; ++e) v[e] = lld<float>(lds, ((kh + 8 * q + e) * 260 + n) * 4);
;             u32x4 w; w.x = pk2(v[0], v[1]); w.y = pk2(v[2], v[3]); w.z = pk2(v[4], v[5]); w.w = pk2(v[6], v[7]);
;             *(u32x4*)(J.Wt + (size_t)(n0d + n) * J.K + k0 + kh + 8 * q) = w; } }
; __global__ void __launch_bounds__(512) mega(Params p) {
;     ...
;             for (int g = bid_(); g < c6; g += gridDim.x) {
;                 ConvJob J;
;                 if (g < c1)      { J = ConvJob{Win, Wt_in, nullptr, 1024, ldw, NIN, even ? 2048 : (1 << 30), even ? 2048 : 0, even ? 3072 : 0}; conv_tile(J, g, lds); }
;                 else if (g < c2) { J = ConvJob{(even ? p.in[16] : p.in[19]) + (size_t)j * 1024 * 1024, Wt_out, nullptr, 1024, 1024, 1024, 1 << 30, 0, 0}; conv_tile(J, g - c1, lds); }
;                 else if (g < c3) { J = ConvJob{p.in[20] + (size_t)L * 1024 * 4096, Wt_up, p.in[4] + L * 1024, 1024, 4096, 4096, 1 << 30, 0, 0}; conv_tile(J, g - c2, lds); }
;                 else if (g < c4) { J = ConvJob{p.in[21] + (size_t)L * 4096 * 1024, Wt_down, nullptr, 4096, 1024, 1024, 1 << 30, 0, 0}; conv_tile(J, g - c3, lds); }
;                 else if (g < c5) { J = ConvJob{p.in[22] + (size_t)L * 256 * 1024, Wt_ple, nullptr, 256, 1024, 1024, 1 << 30, 0, 0}; conv_tile(J, g - c4, lds); }
;                 else             { J = ConvJob{p.in[23] + (size_t)L * 1024 * 1024, Wt_gate, nullptr, 1024, 1024, 1024, 1 << 30, 0, 0}; conv_tile(J, g - c5, lds); }
.LBB0_109:
	s_andn2_b64 vcc, exec, s[2:3]
	s_cbranch_vccnz .LBB0_111
	s_add_i32 s2, s50, s56
	s_addk_i32 s2, 0xfdc0
	s_ashr_i32 s3, s2, 31
	s_lshr_b32 s3, s3, 30
	s_add_i32 s3, s2, s3
	s_and_b32 s38, s3, 0x3fffffc
	v_mov_b32_e32 v34, v194
	s_sub_i32 s2, s2, s38
	s_lshl_b32 s2, s2, 6
	s_lshl_b32 s3, s3, 6
	v_ashrrev_i32_e32 v35, 6, v34
	v_lshlrev_b32_e32 v0, 2, v34
	s_and_b32 s3, s3, 0xffffff00
	v_and_b32_e32 v0, 0xfc, v0
	v_add_u32_e32 v26, s2, v35
	v_or_b32_e32 v2, s3, v0
	v_ashrrev_i32_e32 v27, 31, v26
	v_lshlrev_b64 v[4:5], 12, v[26:27]
	v_ashrrev_i32_e32 v3, 31, v2
	v_lshl_add_u64 v[4:5], s[40:41], 0, v[4:5]
	v_lshlrev_b64 v[28:29], 2, v[2:3]
	v_lshl_add_u64 v[2:3], v[4:5], 0, v[28:29]
	v_add_u32_e32 v4, 8, v26
	v_add_u32_e32 v10, 16, v26
	v_add_u32_e32 v12, 24, v26
	v_add_u32_e32 v18, 32, v26
	v_add_u32_e32 v20, 40, v26
	v_add_u32_e32 v30, 48, v26
	v_add_u32_e32 v26, 56, v26
	v_ashrrev_i32_e32 v5, 31, v4
	v_ashrrev_i32_e32 v11, 31, v10
	v_ashrrev_i32_e32 v13, 31, v12
	v_ashrrev_i32_e32 v19, 31, v18
	v_ashrrev_i32_e32 v21, 31, v20
	v_ashrrev_i32_e32 v31, 31, v30
	v_ashrrev_i32_e32 v27, 31, v26
	v_lshlrev_b64 v[4:5], 12, v[4:5]
	v_lshlrev_b64 v[10:11], 12, v[10:11]
	v_lshlrev_b64 v[12:13], 12, v[12:13]
	v_lshlrev_b64 v[18:19], 12, v[18:19]
	v_lshlrev_b64 v[20:21], 12, v[20:21]
	v_lshlrev_b64 v[30:31], 12, v[30:31]
	v_lshlrev_b64 v[26:27], 12, v[26:27]
	v_lshl_add_u64 v[4:5], s[40:41], 0, v[4:5]
	v_lshl_add_u64 v[10:11], s[40:41], 0, v[10:11]
	v_lshl_add_u64 v[12:13], s[40:41], 0, v[12:13]
	v_lshl_add_u64 v[18:19], s[40:41], 0, v[18:19]
	v_lshl_add_u64 v[20:21], s[40:41], 0, v[20:21]
	v_lshl_add_u64 v[30:31], s[40:41], 0, v[30:31]
	v_lshl_add_u64 v[26:27], s[40:41], 0, v[26:27]
	v_lshl_add_u64 v[6:7], v[4:5], 0, v[28:29]
	v_lshl_add_u64 v[10:11], v[10:11], 0, v[28:29]
	v_lshl_add_u64 v[14:15], v[12:13], 0, v[28:29]
	v_lshl_add_u64 v[18:19], v[18:19], 0, v[28:29]
	v_lshl_add_u64 v[22:23], v[20:21], 0, v[28:29]
	v_lshl_add_u64 v[30:31], v[30:31], 0, v[28:29]
	v_lshl_add_u64 v[32:33], v[26:27], 0, v[28:29]
	global_load_dwordx4 v[2:5], v[2:3], off nt
	s_nop 0
	global_load_dwordx4 v[6:9], v[6:7], off nt
	s_nop 0
	global_load_dwordx4 v[10:13], v[10:11], off nt
	s_nop 0
	global_load_dwordx4 v[14:17], v[14:15], off nt
	s_nop 0
	global_load_dwordx4 v[18:21], v[18:19], off nt
	s_nop 0
	global_load_dwordx4 v[22:25], v[22:23], off nt
	s_nop 0
	global_load_dwordx4 v[26:29], v[30:31], off nt
	s_nop 0
	global_load_dwordx4 v[30:33], v[32:33], off nt
	v_ashrrev_i32_e32 v36, 1, v34
	v_lshlrev_b32_e32 v34, 5, v34
	v_and_b32_e32 v37, 32, v34
	s_movk_i32 s36, 0x104
	v_mad_u64_u32 v[34:35], s[38:39], v35, s36, v[0:1]
	v_mad_u32_u24 v0, v37, s36, v36
	v_lshl_add_u32 v38, v34, 2, 0
	v_lshl_add_u32 v39, v0, 2, 0
	v_add_u32_e32 v34, s3, v36
	v_ashrrev_i32_e32 v35, 31, v34
	v_readlane_b32 s36, v250, 51
	v_readlane_b32 s37, v250, 52
	s_ashr_i32 s3, s2, 31
	s_waitcnt vmcnt(7)
	ds_write_b128 v38, v[2:5]
	s_waitcnt vmcnt(6)
	ds_write_b128 v38, v[6:9] offset:8320
	s_waitcnt vmcnt(5)
	ds_write_b128 v38, v[10:13] offset:16640
	s_waitcnt vmcnt(4)
	ds_write_b128 v38, v[14:17] offset:24960
	s_waitcnt vmcnt(3)
	ds_write_b128 v38, v[18:21] offset:33280
	s_waitcnt vmcnt(2)
	ds_write_b128 v38, v[22:25] offset:41600
	s_waitcnt vmcnt(1)
	ds_write_b128 v38, v[26:29] offset:49920
	s_waitcnt vmcnt(0)
	ds_write_b128 v38, v[30:33] offset:58240
	s_waitcnt lgkmcnt(0)
	s_barrier
	ds_read_b32 v0, v39
	ds_read_b32 v2, v39 offset:1040
	ds_read_b32 v3, v39 offset:2080
	ds_read_b32 v4, v39 offset:3120
	ds_read_b32 v5, v39 offset:4160
	ds_read_b32 v6, v39 offset:5200
	ds_read_b32 v7, v39 offset:6240
	ds_read_b32 v8, v39 offset:7280
	s_waitcnt lgkmcnt(4)
	v_cvt_pk_bf16_f32 v3, v3, v4
	v_cvt_pk_bf16_f32 v2, v0, v2
	s_waitcnt lgkmcnt(2)
	v_cvt_pk_bf16_f32 v4, v5, v6
	v_lshlrev_b32_e32 v0, 1, v37
	s_waitcnt lgkmcnt(0)
	v_cvt_pk_bf16_f32 v5, v7, v8
	v_lshlrev_b64 v[6:7], 9, v[34:35]
	v_lshl_add_u64 v[6:7], s[36:37], 0, v[6:7]
	v_lshl_add_u64 v[6:7], s[2:3], 1, v[6:7]
	v_lshl_add_u64 v[6:7], v[6:7], 0, v[0:1]
	ds_read_b32 v0, v39 offset:8320
	ds_read_b32 v8, v39 offset:9360
	ds_read_b32 v9, v39 offset:10400
	ds_read_b32 v10, v39 offset:11440
	ds_read_b32 v11, v39 offset:12480
	ds_read_b32 v12, v39 offset:13520
	ds_read_b32 v13, v39 offset:14560
	ds_read_b32 v14, v39 offset:15600
	global_store_dwordx4 v[6:7], v[2:5], off
	s_waitcnt lgkmcnt(6)
	s_nop 0
	v_cvt_pk_bf16_f32 v2, v0, v8
	s_waitcnt lgkmcnt(4)
	v_cvt_pk_bf16_f32 v3, v9, v10
	s_waitcnt lgkmcnt(2)
	v_cvt_pk_bf16_f32 v4, v11, v12
	s_waitcnt lgkmcnt(0)
	v_cvt_pk_bf16_f32 v5, v13, v14
	ds_read_b32 v0, v39 offset:16640
	ds_read_b32 v8, v39 offset:17680
	ds_read_b32 v9, v39 offset:18720
	ds_read_b32 v10, v39 offset:19760
	ds_read_b32 v11, v39 offset:20800
	ds_read_b32 v12, v39 offset:21840
	ds_read_b32 v13, v39 offset:22880
	ds_read_b32 v14, v39 offset:23920
	global_store_dwordx4 v[6:7], v[2:5], off offset:16
	s_waitcnt lgkmcnt(6)
	s_nop 0
	v_cvt_pk_bf16_f32 v2, v0, v8
	s_waitcnt lgkmcnt(4)
	v_cvt_pk_bf16_f32 v3, v9, v10
	s_waitcnt lgkmcnt(2)
	v_cvt_pk_bf16_f32 v4, v11, v12
	s_waitcnt lgkmcnt(0)
	v_cvt_pk_bf16_f32 v5, v13, v14
	ds_read_b32 v0, v39 offset:24960
	ds_read_b32 v8, v39 offset:26000
	ds_read_b32 v9, v39 offset:27040
	ds_read_b32 v10, v39 offset:28080
	ds_read_b32 v11, v39 offset:29120
	ds_read_b32 v12, v39 offset:30160
	ds_read_b32 v13, v39 offset:31200
	ds_read_b32 v14, v39 offset:32240
	global_store_dwordx4 v[6:7], v[2:5], off offset:32
	s_waitcnt lgkmcnt(6)
	s_nop 0
	v_cvt_pk_bf16_f32 v2, v0, v8
	s_waitcnt lgkmcnt(4)
	v_cvt_pk_bf16_f32 v3, v9, v10
	s_waitcnt lgkmcnt(2)
	v_cvt_pk_bf16_f32 v4, v11, v12
	s_waitcnt lgkmcnt(0)
	v_cvt_pk_bf16_f32 v5, v13, v14
	global_store_dwordx4 v[6:7], v[2:5], off offset:48
	s_barrier

; DI void conv_tile(const ConvJob& J, int t, lptr lds) {
;     const int tid = tid_(); const int nkt = J.K / 64;
;     const int kt = t % nkt, nt = t / nkt; const int k0 = kt * 64, n0d = nt * 256, n0s = n0d + (n0d >= J.split ? 8 : 0);
; #pragma unroll
;     for (int it = 0; it < 8; ++it) { const int kr = it * 8 + (tid >> 6), nc = (tid & 63) * 4;
;         int scol = n0s + nc;
;         if (n0d >= J.rlo && n0d < J.rhi) { const int d = n0d + nc - J.rlo, jj = d & 63, chunk = jj >> 3; scol = J.rlo + (n0s - n0d) + (d & ~63) + ((jj & 4) ? 32 + 4 * chunk : 4 * chunk); }
;         const f32x4 v = *(const f32x4*)(J.W + (size_t)(k0 + kr) * J.ldn + scol);
;         const float rsc = J.rs ? J.rs[k0 + kr] : 1.f;
;         lst<f32x4>(lds, (kr * 260 + nc) * 4, v * rsc); }
;     __syncthreads();
;     { const int n = tid >> 1, kh = (tid & 1) * 32;
; #pragma unroll
;         for (int q = 0; q < 4; ++q) { float v[8];
;             for (int e = 0; e < 8; ++e) v[e] = lld<float>(lds, ((kh + 8 * q + e) * 260 + n) * 4);
;             u32x4 w; w.x = pk2(v[0], v[1]); w.y = pk2(v[2], v[3]); w.z = pk2(v[4], v[5]); w.w = pk2(v[6], v[7]);
;             *(u32x4*)(J.Wt + (size_t)(n0d + n) * J.K + k0 + kh + 8 * q) = w; } }
; __global__ void __launch_bounds__(512) mega(Params p) {
;     ...
;             for (int g = bid_(); g < c6; g += gridDim.x) {
;                 ConvJob J;
;                 if (g < c1)      { J = ConvJob{Win, Wt_in, nullptr, 1024, ldw, NIN, even ? 2048 : (1 << 30), even ? 2048 : 0, even ? 3072 : 0}; conv_tile(J, g, lds); }
;                 else if (g < c2) { J = ConvJob{(even ? p.in[16] : p.in[19]) + (size_t)j * 1024 * 1024, Wt_out, nullptr, 1024, 1024, 1024, 1 << 30, 0, 0}; conv_tile(J, g - c1, lds); }
;                 else if (g < c3) { J = ConvJob{p.in[20] + (size_t)L * 1024 * 4096, Wt_up, p.in[4] + L * 1024, 1024, 4096, 4096, 1 << 30, 0, 0}; conv_tile(J, g - c2, lds); }
;                 else if (g < c4) { J = ConvJob{p.in[21] + (size_t)L * 4096 * 1024, Wt_down, nullptr, 4096, 1024, 1024, 1 << 30, 0, 0}; conv_tile(J, g - c3, lds); }
;                 else if (g < c5) { J = ConvJob{p.in[22] + (size_t)L * 256 * 1024, Wt_ple, nullptr, 256, 1024, 1024, 1 << 30, 0, 0}; conv_tile(J, g - c4, lds); }
;                 else             { J = ConvJob{p.in[23] + (size_t)L * 1024 * 1024, Wt_gate, nullptr, 1024, 1024, 1024, 1 << 30, 0, 0}; conv_tile(J, g - c5, lds); }
.LBB0_112:
	s_andn2_b64 vcc, exec, s[2:3]
	s_cbranch_vccnz .LBB0_114
	s_add_i32 s2, s50, s56
	s_addk_i32 s2, 0xfec0
	s_ashr_i32 s3, s2, 31
	s_lshr_b32 s3, s3, 26
	s_add_i32 s3, s2, s3
	s_and_b32 s38, s3, 0x3ffffc0
	v_mov_b32_e32 v35, v194
	s_sub_i32 s2, s2, s38
	s_lshl_b32 s2, s2, 6
	v_ashrrev_i32_e32 v36, 6, v35
	v_add_u32_e32 v26, s2, v36
	v_ashrrev_i32_e32 v27, 31, v26
	s_lshl_b32 s3, s3, 2
	v_lshlrev_b32_e32 v0, 2, v35
	v_lshlrev_b64 v[2:3], 12, v[26:27]
	v_add_u32_e32 v4, 8, v26
	v_add_u32_e32 v10, 16, v26
	v_add_u32_e32 v12, 24, v26
	v_add_u32_e32 v18, 32, v26
	v_add_u32_e32 v20, 40, v26
	v_add_u32_e32 v30, 48, v26
	v_add_u32_e32 v26, 56, v26
	s_and_b32 s3, s3, 0xffffff00
	v_and_b32_e32 v34, 0xfc, v0
	v_ashrrev_i32_e32 v5, 31, v4
	v_ashrrev_i32_e32 v11, 31, v10
	v_ashrrev_i32_e32 v13, 31, v12
	v_ashrrev_i32_e32 v19, 31, v18
	v_ashrrev_i32_e32 v21, 31, v20
	v_ashrrev_i32_e32 v31, 31, v30
	v_ashrrev_i32_e32 v27, 31, v26
	v_or_b32_e32 v0, s3, v34
	v_lshlrev_b64 v[4:5], 12, v[4:5]
	v_lshlrev_b64 v[10:11], 12, v[10:11]
	v_lshlrev_b64 v[12:13], 12, v[12:13]
	v_lshlrev_b64 v[18:19], 12, v[18:19]
	v_lshlrev_b64 v[20:21], 12, v[20:21]
	v_lshlrev_b64 v[30:31], 12, v[30:31]
	v_lshlrev_b64 v[26:27], 12, v[26:27]
	v_lshl_add_u64 v[2:3], s[42:43], 0, v[2:3]
	v_lshlrev_b64 v[28:29], 2, v[0:1]
	v_lshl_add_u64 v[4:5], s[42:43], 0, v[4:5]
	v_lshl_add_u64 v[10:11], s[42:43], 0, v[10:11]
	v_lshl_add_u64 v[12:13], s[42:43], 0, v[12:13]
	v_lshl_add_u64 v[18:19], s[42:43], 0, v[18:19]
	v_lshl_add_u64 v[20:21], s[42:43], 0, v[20:21]
	v_lshl_add_u64 v[30:31], s[42:43], 0, v[30:31]
	v_lshl_add_u64 v[26:27], s[42:43], 0, v[26:27]
	v_lshl_add_u64 v[2:3], v[2:3], 0, v[28:29]
	v_lshl_add_u64 v[6:7], v[4:5], 0, v[28:29]
	v_lshl_add_u64 v[10:11], v[10:11], 0, v[28:29]
	v_lshl_add_u64 v[14:15], v[12:13], 0, v[28:29]
	v_lshl_add_u64 v[18:19], v[18:19], 0, v[28:29]
	v_lshl_add_u64 v[22:23], v[20:21], 0, v[28:29]
	v_lshl_add_u64 v[30:31], v[30:31], 0, v[28:29]
	v_lshl_add_u64 v[32:33], v[26:27], 0, v[28:29]
	global_load_dwordx4 v[2:5], v[2:3], off nt
	s_nop 0
	global_load_dwordx4 v[6:9], v[6:7], off nt
	s_nop 0
	global_load_dwordx4 v[10:13], v[10:11], off nt
	s_nop 0
	global_load_dwordx4 v[14:17], v[14:15], off nt
	s_nop 0
	global_load_dwordx4 v[18:21], v[18:19], off nt
	s_nop 0
	global_load_dwordx4 v[22:25], v[22:23], off nt
	s_nop 0
	global_load_dwordx4 v[26:29], v[30:31], off nt
	s_nop 0
	global_load_dwordx4 v[30:33], v[32:33], off nt
	v_ashrrev_i32_e32 v0, 1, v35
	v_lshlrev_b32_e32 v35, 5, v35
	s_movk_i32 s36, 0x104
	v_and_b32_e32 v37, 32, v35
	v_mad_u64_u32 v[34:35], s[38:39], v36, s36, v[34:35]
	v_mad_u32_u24 v35, v37, s36, v0
	v_lshl_add_u32 v36, v34, 2, 0
	v_lshl_add_u32 v38, v35, 2, 0
	v_add_u32_e32 v34, s3, v0
	v_ashrrev_i32_e32 v35, 31, v34
	v_readlane_b32 s36, v250, 49
	v_readlane_b32 s37, v250, 50
	s_ashr_i32 s3, s2, 31
	s_waitcnt vmcnt(7)
	ds_write_b128 v36, v[2:5]
	s_waitcnt vmcnt(6)
	ds_write_b128 v36, v[6:9] offset:8320
	s_waitcnt vmcnt(5)
	ds_write_b128 v36, v[10:13] offset:16640
	s_waitcnt vmcnt(4)
	ds_write_b128 v36, v[14:17] offset:24960
	s_waitcnt vmcnt(3)
	ds_write_b128 v36, v[18:21] offset:33280
	s_waitcnt vmcnt(2)
	ds_write_b128 v36, v[22:25] offset:41600
	s_waitcnt vmcnt(1)
	ds_write_b128 v36, v[26:29] offset:49920
	s_waitcnt vmcnt(0)
	ds_write_b128 v36, v[30:33] offset:58240
	s_waitcnt lgkmcnt(0)
	s_barrier
	ds_read_b32 v0, v38
	ds_read_b32 v2, v38 offset:1040
	ds_read_b32 v3, v38 offset:2080
	ds_read_b32 v4, v38 offset:3120
	ds_read_b32 v5, v38 offset:4160
	ds_read_b32 v8, v38 offset:5200
	ds_read_b32 v9, v38 offset:6240
	ds_read_b32 v10, v38 offset:7280
	v_lshlrev_b64 v[6:7], 13, v[34:35]
	v_lshl_add_u64 v[6:7], s[36:37], 0, v[6:7]
	s_waitcnt lgkmcnt(6)
	v_cvt_pk_bf16_f32 v2, v0, v2
	v_lshl_add_u64 v[6:7], s[2:3], 1, v[6:7]
	v_lshlrev_b32_e32 v0, 1, v37
	s_waitcnt lgkmcnt(4)
	v_cvt_pk_bf16_f32 v3, v3, v4
	s_waitcnt lgkmcnt(2)
	v_cvt_pk_bf16_f32 v4, v5, v8
	s_waitcnt lgkmcnt(0)
	v_cvt_pk_bf16_f32 v5, v9, v10
	v_lshl_add_u64 v[6:7], v[6:7], 0, v[0:1]
	ds_read_b32 v0, v38 offset:8320
	ds_read_b32 v8, v38 offset:9360
	ds_read_b32 v9, v38 offset:10400
	ds_read_b32 v10, v38 offset:11440
	ds_read_b32 v11, v38 offset:12480
	ds_read_b32 v12, v38 offset:13520
	ds_read_b32 v13, v38 offset:14560
	ds_read_b32 v14, v38 offset:15600
	global_store_dwordx4 v[6:7], v[2:5], off
	s_waitcnt lgkmcnt(6)
	s_nop 0
	v_cvt_pk_bf16_f32 v2, v0, v8
	s_waitcnt lgkmcnt(4)
	v_cvt_pk_bf16_f32 v3, v9, v10
	s_waitcnt lgkmcnt(2)
	v_cvt_pk_bf16_f32 v4, v11, v12
	s_waitcnt lgkmcnt(0)
	v_cvt_pk_bf16_f32 v5, v13, v14
	ds_read_b32 v0, v38 offset:16640
	ds_read_b32 v8, v38 offset:17680
	ds_read_b32 v9, v38 offset:18720
	ds_read_b32 v10, v38 offset:19760
	ds_read_b32 v11, v38 offset:20800
	ds_read_b32 v12, v38 offset:21840
	ds_read_b32 v13, v38 offset:22880
	ds_read_b32 v14, v38 offset:23920
	global_store_dwordx4 v[6:7], v[2:5], off offset:16
	s_waitcnt lgkmcnt(6)
	s_nop 0
	v_cvt_pk_bf16_f32 v2, v0, v8
	s_waitcnt lgkmcnt(4)
	v_cvt_pk_bf16_f32 v3, v9, v10
	s_waitcnt lgkmcnt(2)
	v_cvt_pk_bf16_f32 v4, v11, v12
	s_waitcnt lgkmcnt(0)
	v_cvt_pk_bf16_f32 v5, v13, v14
	ds_read_b32 v0, v38 offset:24960
	ds_read_b32 v8, v38 offset:26000
	ds_read_b32 v9, v38 offset:27040
	ds_read_b32 v10, v38 offset:28080
	ds_read_b32 v11, v38 offset:29120
	ds_read_b32 v12, v38 offset:30160
	ds_read_b32 v13, v38 offset:31200
	ds_read_b32 v14, v38 offset:32240
	global_store_dwordx4 v[6:7], v[2:5], off offset:32
	s_waitcnt lgkmcnt(6)
	s_nop 0
	v_cvt_pk_bf16_f32 v2, v0, v8
	s_waitcnt lgkmcnt(4)
	v_cvt_pk_bf16_f32 v3, v9, v10
	s_waitcnt lgkmcnt(2)
	v_cvt_pk_bf16_f32 v4, v11, v12
	s_waitcnt lgkmcnt(0)
	v_cvt_pk_bf16_f32 v5, v13, v14
	global_store_dwordx4 v[6:7], v[2:5], off offset:48
	s_barrier

; DI unsigned pk2(float lo, float hi) { f32x2_t v = {lo, hi}; bf16x2_t b = __builtin_convertvector(v, bf16x2_t); return __builtin_bit_cast(unsigned, b); }
; DI void conv_tile(const ConvJob& J, int t, lptr lds) {
;     ...
; #pragma unroll
;     for (int it = 0; it < 8; ++it) { const int kr = it * 8 + (tid >> 6), nc = (tid & 63) * 4;
;         int scol = n0s + nc;
;         if (n0d >= J.rlo && n0d < J.rhi) { const int d = n0d + nc - J.rlo, jj = d & 63, chunk = jj >> 3; scol = J.rlo + (n0s - n0d) + (d & ~63) + ((jj & 4) ? 32 + 4 * chunk : 4 * chunk); }
;         const f32x4 v = *(const f32x4*)(J.W + (size_t)(k0 + kr) * J.ldn + scol);
;         const float rsc = J.rs ? J.rs[k0 + kr] : 1.f;
;         lst<f32x4>(lds, (kr * 260 + nc) * 4, v * rsc); }
;     __syncthreads();
;     { const int n = tid >> 1, kh = (tid & 1) * 32;
; #pragma unroll
;         for (int q = 0; q < 4; ++q) { float v[8];
;             for (int e = 0; e < 8; ++e) v[e] = lld<float>(lds, ((kh + 8 * q + e) * 260 + n) * 4);
;             u32x4 w; w.x = pk2(v[0], v[1]); w.y = pk2(v[2], v[3]); w.z = pk2(v[4], v[5]); w.w = pk2(v[6], v[7]);
;             *(u32x4*)(J.Wt + (size_t)(n0d + n) * J.K + k0 + kh + 8 * q) = w; } }
;     __syncthreads();
.Lmy_up_nors:
	global_load_dwordx4 v[96:99], v[2:3], off nt
	v_add_u32_e32 v6, 8, v12
	v_ashrrev_i32_e32 v7, 31, v6
	v_lshlrev_b64 v[6:7], 14, v[6:7]
	v_lshl_add_u64 v[6:7], s[44:45], 0, v[6:7]
	v_lshl_add_u64 v[6:7], v[10:11], 2, v[6:7]
	global_load_dwordx4 v[100:103], v[6:7], off nt
	v_add_u32_e32 v6, 16, v12
	v_ashrrev_i32_e32 v7, 31, v6
	v_lshlrev_b64 v[6:7], 14, v[6:7]
	v_lshl_add_u64 v[6:7], s[44:45], 0, v[6:7]
	v_lshl_add_u64 v[6:7], v[10:11], 2, v[6:7]
	global_load_dwordx4 v[104:107], v[6:7], off nt
	v_add_u32_e32 v6, 24, v12
	v_ashrrev_i32_e32 v7, 31, v6
	v_lshlrev_b64 v[6:7], 14, v[6:7]
	v_lshl_add_u64 v[6:7], s[44:45], 0, v[6:7]
	v_lshl_add_u64 v[6:7], v[10:11], 2, v[6:7]
	global_load_dwordx4 v[108:111], v[6:7], off nt
	v_add_u32_e32 v6, 32, v12
	v_ashrrev_i32_e32 v7, 31, v6
	v_lshlrev_b64 v[6:7], 14, v[6:7]
	v_lshl_add_u64 v[6:7], s[44:45], 0, v[6:7]
	v_lshl_add_u64 v[6:7], v[10:11], 2, v[6:7]
	global_load_dwordx4 v[112:115], v[6:7], off nt
	v_add_u32_e32 v6, 40, v12
	v_ashrrev_i32_e32 v7, 31, v6
	v_lshlrev_b64 v[6:7], 14, v[6:7]
	v_lshl_add_u64 v[6:7], s[44:45], 0, v[6:7]
	v_lshl_add_u64 v[6:7], v[10:11], 2, v[6:7]
	global_load_dwordx4 v[116:119], v[6:7], off nt
	v_add_u32_e32 v6, 48, v12
	v_ashrrev_i32_e32 v7, 31, v6
	v_lshlrev_b64 v[6:7], 14, v[6:7]
	v_lshl_add_u64 v[6:7], s[44:45], 0, v[6:7]
	v_lshl_add_u64 v[6:7], v[10:11], 2, v[6:7]
	global_load_dwordx4 v[120:123], v[6:7], off nt
	v_add_u32_e32 v6, 56, v12
	v_ashrrev_i32_e32 v7, 31, v6
	v_lshlrev_b64 v[6:7], 14, v[6:7]
	v_lshl_add_u64 v[6:7], s[44:45], 0, v[6:7]
	v_lshl_add_u64 v[6:7], v[10:11], 2, v[6:7]
	global_load_dwordx4 v[124:127], v[6:7], off nt
	s_movk_i32 s36, 0x104
	v_mad_u64_u32 v[16:17], s[58:59], v17, s36, v[16:17]
	v_lshl_add_u32 v13, v16, 2, 0
	s_waitcnt vmcnt(7)
	v_pk_mul_f32 v[96:97], v[96:97], v[128:129] op_sel_hi:[1,0]
	v_pk_mul_f32 v[98:99], v[98:99], v[128:129] op_sel_hi:[1,0]
	ds_write_b128 v13, v[96:99]
	s_waitcnt vmcnt(6)
	v_pk_mul_f32 v[100:101], v[100:101], v[130:131] op_sel_hi:[1,0]
	v_pk_mul_f32 v[102:103], v[102:103], v[130:131] op_sel_hi:[1,0]
	ds_write_b128 v13, v[100:103] offset:8320
	s_waitcnt vmcnt(5)
	v_pk_mul_f32 v[104:105], v[104:105], v[132:133] op_sel_hi:[1,0]
	v_pk_mul_f32 v[106:107], v[106:107], v[132:133] op_sel_hi:[1,0]
	ds_write_b128 v13, v[104:107] offset:16640
	s_waitcnt vmcnt(4)
	v_pk_mul_f32 v[108:109], v[108:109], v[136:137] op_sel_hi:[1,0]
	v_pk_mul_f32 v[110:111], v[110:111], v[136:137] op_sel_hi:[1,0]
	ds_write_b128 v13, v[108:111] offset:24960
	s_waitcnt vmcnt(3)
	v_pk_mul_f32 v[112:113], v[112:113], v[138:139] op_sel_hi:[1,0]
	v_pk_mul_f32 v[114:115], v[114:115], v[138:139] op_sel_hi:[1,0]
	ds_write_b128 v13, v[112:115] offset:33280
	s_waitcnt vmcnt(2)
	v_pk_mul_f32 v[116:117], v[116:117], v[140:141] op_sel_hi:[1,0]
	v_pk_mul_f32 v[118:119], v[118:119], v[140:141] op_sel_hi:[1,0]
	ds_write_b128 v13, v[116:119] offset:41600
	s_waitcnt vmcnt(1)
	v_pk_mul_f32 v[120:121], v[120:121], v[142:143] op_sel_hi:[1,0]
	v_pk_mul_f32 v[122:123], v[122:123], v[142:143] op_sel_hi:[1,0]
	ds_write_b128 v13, v[120:123] offset:49920
	s_waitcnt vmcnt(0)
	v_pk_mul_f32 v[124:125], v[124:125], v[144:145] op_sel_hi:[1,0]
	v_pk_mul_f32 v[126:127], v[126:127], v[144:145] op_sel_hi:[1,0]
	ds_write_b128 v13, v[124:127] offset:58240
	v_ashrrev_i32_e32 v0, 1, v19
	v_lshlrev_b32_e32 v2, 5, v19
	v_and_b32_e32 v8, 32, v2
	v_add_u32_e32 v6, s3, v0
	s_movk_i32 s3, 0x104
	v_mad_u32_u24 v0, v8, s3, v0
	v_lshl_add_u32 v9, v0, 2, 0
	s_waitcnt lgkmcnt(0)
	s_barrier
	ds_read_b32 v0, v9
	ds_read_b32 v2, v9 offset:1040
	ds_read_b32 v3, v9 offset:2080
	ds_read_b32 v4, v9 offset:3120
	ds_read_b32 v5, v9 offset:4160
	ds_read_b32 v10, v9 offset:5200
	ds_read_b32 v11, v9 offset:6240
	ds_read_b32 v12, v9 offset:7280
	v_ashrrev_i32_e32 v7, 31, v6
	v_readlane_b32 s36, v250, 47
	v_lshlrev_b64 v[6:7], 11, v[6:7]
	v_readlane_b32 s37, v250, 48
	s_ashr_i32 s3, s2, 31
	s_waitcnt lgkmcnt(6)
	v_cvt_pk_bf16_f32 v2, v0, v2
	v_lshl_add_u64 v[6:7], s[36:37], 0, v[6:7]
	v_lshl_add_u64 v[6:7], s[2:3], 1, v[6:7]
	v_lshlrev_b32_e32 v0, 1, v8
	s_waitcnt lgkmcnt(4)
	v_cvt_pk_bf16_f32 v3, v3, v4
	s_waitcnt lgkmcnt(2)
	v_cvt_pk_bf16_f32 v4, v5, v10
	s_waitcnt lgkmcnt(0)
	v_cvt_pk_bf16_f32 v5, v11, v12
	v_lshl_add_u64 v[6:7], v[6:7], 0, v[0:1]
	ds_read_b32 v0, v9 offset:8320
	ds_read_b32 v8, v9 offset:9360
	ds_read_b32 v10, v9 offset:10400
	ds_read_b32 v11, v9 offset:11440
	ds_read_b32 v12, v9 offset:12480
	ds_read_b32 v13, v9 offset:13520
	ds_read_b32 v14, v9 offset:14560
	ds_read_b32 v15, v9 offset:15600
	global_store_dwordx4 v[6:7], v[2:5], off
	s_waitcnt lgkmcnt(6)
	s_nop 0
	v_cvt_pk_bf16_f32 v2, v0, v8
	s_waitcnt lgkmcnt(4)
	v_cvt_pk_bf16_f32 v3, v10, v11
	s_waitcnt lgkmcnt(2)
	v_cvt_pk_bf16_f32 v4, v12, v13
	s_waitcnt lgkmcnt(0)
	v_cvt_pk_bf16_f32 v5, v14, v15
	ds_read_b32 v0, v9 offset:16640
	ds_read_b32 v8, v9 offset:17680
	ds_read_b32 v10, v9 offset:18720
	ds_read_b32 v11, v9 offset:19760
	ds_read_b32 v12, v9 offset:20800
	ds_read_b32 v13, v9 offset:21840
	ds_read_b32 v14, v9 offset:22880
	ds_read_b32 v15, v9 offset:23920
	global_store_dwordx4 v[6:7], v[2:5], off offset:16
	s_waitcnt lgkmcnt(6)
	s_nop 0
	v_cvt_pk_bf16_f32 v2, v0, v8
	s_waitcnt lgkmcnt(4)
	v_cvt_pk_bf16_f32 v3, v10, v11
	s_waitcnt lgkmcnt(2)
	v_cvt_pk_bf16_f32 v4, v12, v13
	s_waitcnt lgkmcnt(0)
	v_cvt_pk_bf16_f32 v5, v14, v15
	ds_read_b32 v0, v9 offset:24960
	ds_read_b32 v8, v9 offset:26000
	ds_read_b32 v10, v9 offset:27040
	ds_read_b32 v11, v9 offset:28080
	ds_read_b32 v12, v9 offset:29120
	ds_read_b32 v13, v9 offset:30160
	ds_read_b32 v14, v9 offset:31200
	ds_read_b32 v9, v9 offset:32240
	global_store_dwordx4 v[6:7], v[2:5], off offset:32
	s_waitcnt lgkmcnt(6)
	s_nop 0
	v_cvt_pk_bf16_f32 v2, v0, v8
	s_waitcnt lgkmcnt(4)
	v_cvt_pk_bf16_f32 v3, v10, v11
	s_waitcnt lgkmcnt(2)
	v_cvt_pk_bf16_f32 v4, v12, v13
	s_waitcnt lgkmcnt(0)
	v_cvt_pk_bf16_f32 v5, v14, v9
	global_store_dwordx4 v[6:7], v[2:5], off offset:48
	s_barrier

; DI void conv_tile(const ConvJob& J, int t, lptr lds) {
;     const int tid = tid_(); const int nkt = J.K / 64;
;     const int kt = t % nkt, nt = t / nkt; const int k0 = kt * 64, n0d = nt * 256, n0s = n0d + (n0d >= J.split ? 8 : 0);
; #pragma unroll
;     for (int it = 0; it < 8; ++it) { const int kr = it * 8 + (tid >> 6), nc = (tid & 63) * 4;
;         int scol = n0s + nc;
;         if (n0d >= J.rlo && n0d < J.rhi) { const int d = n0d + nc - J.rlo, jj = d & 63, chunk = jj >> 3; scol = J.rlo + (n0s - n0d) + (d & ~63) + ((jj & 4) ? 32 + 4 * chunk : 4 * chunk); }
;         const f32x4 v = *(const f32x4*)(J.W + (size_t)(k0 + kr) * J.ldn + scol);
;         const float rsc = J.rs ? J.rs[k0 + kr] : 1.f;
;         lst<f32x4>(lds, (kr * 260 + nc) * 4, v * rsc); }
;     __syncthreads();
;     { const int n = tid >> 1, kh = (tid & 1) * 32;
; #pragma unroll
;         for (int q = 0; q < 4; ++q) { float v[8];
;             for (int e = 0; e < 8; ++e) v[e] = lld<float>(lds, ((kh + 8 * q + e) * 260 + n) * 4);
;             u32x4 w; w.x = pk2(v[0], v[1]); w.y = pk2(v[2], v[3]); w.z = pk2(v[4], v[5]); w.w = pk2(v[6], v[7]);
;             *(u32x4*)(J.Wt + (size_t)(n0d + n) * J.K + k0 + kh + 8 * q) = w; } }
; __global__ void __launch_bounds__(512) mega(Params p) {
;     ...
;             for (int g = bid_(); g < c6; g += gridDim.x) {
;                 ConvJob J;
;                 if (g < c1)      { J = ConvJob{Win, Wt_in, nullptr, 1024, ldw, NIN, even ? 2048 : (1 << 30), even ? 2048 : 0, even ? 3072 : 0}; conv_tile(J, g, lds); }
;                 else if (g < c2) { J = ConvJob{(even ? p.in[16] : p.in[19]) + (size_t)j * 1024 * 1024, Wt_out, nullptr, 1024, 1024, 1024, 1 << 30, 0, 0}; conv_tile(J, g - c1, lds); }
;                 else if (g < c3) { J = ConvJob{p.in[20] + (size_t)L * 1024 * 4096, Wt_up, p.in[4] + L * 1024, 1024, 4096, 4096, 1 << 30, 0, 0}; conv_tile(J, g - c2, lds); }
;                 else if (g < c4) { J = ConvJob{p.in[21] + (size_t)L * 4096 * 1024, Wt_down, nullptr, 4096, 1024, 1024, 1 << 30, 0, 0}; conv_tile(J, g - c3, lds); }
;                 else if (g < c5) { J = ConvJob{p.in[22] + (size_t)L * 256 * 1024, Wt_ple, nullptr, 256, 1024, 1024, 1 << 30, 0, 0}; conv_tile(J, g - c4, lds); }
;                 else             { J = ConvJob{p.in[23] + (size_t)L * 1024 * 1024, Wt_gate, nullptr, 1024, 1024, 1024, 1 << 30, 0, 0}; conv_tile(J, g - c5, lds); }
.LBB0_134:
	s_andn2_b64 vcc, exec, s[2:3]
	s_cbranch_vccnz .LBB0_136
	s_add_i32 s2, s50, s56
	s_ashr_i32 s3, s2, 31
	s_lshr_b32 s3, s3, 28
	s_add_i32 s3, s2, s3
	s_and_b32 s38, s3, 0x3fffff0
	v_mov_b32_e32 v34, v194
	s_sub_i32 s2, s2, s38
	s_lshl_b32 s2, s2, 6
	s_lshl_b32 s3, s3, 4
	v_ashrrev_i32_e32 v35, 6, v34
	v_lshlrev_b32_e32 v0, 2, v34
	s_and_b32 s3, s3, 0xffffff00
	v_and_b32_e32 v0, 0xfc, v0
	v_add_u32_e32 v26, s2, v35
	v_or_b32_e32 v2, s3, v0
	v_ashrrev_i32_e32 v27, 31, v26
	v_lshlrev_b64 v[4:5], 12, v[26:27]
	v_ashrrev_i32_e32 v3, 31, v2
	v_lshl_add_u64 v[4:5], s[48:49], 0, v[4:5]
	v_lshlrev_b64 v[28:29], 2, v[2:3]
	v_lshl_add_u64 v[2:3], v[4:5], 0, v[28:29]
	v_add_u32_e32 v4, 8, v26
	v_add_u32_e32 v10, 16, v26
	v_add_u32_e32 v12, 24, v26
	v_add_u32_e32 v18, 32, v26
	v_add_u32_e32 v20, 40, v26
	v_add_u32_e32 v30, 48, v26
	v_add_u32_e32 v26, 56, v26
	v_ashrrev_i32_e32 v5, 31, v4
	v_ashrrev_i32_e32 v11, 31, v10
	v_ashrrev_i32_e32 v13, 31, v12
	v_ashrrev_i32_e32 v19, 31, v18
	v_ashrrev_i32_e32 v21, 31, v20
	v_ashrrev_i32_e32 v31, 31, v30
	v_ashrrev_i32_e32 v27, 31, v26
	v_lshlrev_b64 v[4:5], 12, v[4:5]
	v_lshlrev_b64 v[10:11], 12, v[10:11]
	v_lshlrev_b64 v[12:13], 12, v[12:13]
	v_lshlrev_b64 v[18:19], 12, v[18:19]
	v_lshlrev_b64 v[20:21], 12, v[20:21]
	v_lshlrev_b64 v[30:31], 12, v[30:31]
	v_lshlrev_b64 v[26:27], 12, v[26:27]
	v_lshl_add_u64 v[4:5], s[48:49], 0, v[4:5]
	v_lshl_add_u64 v[10:11], s[48:49], 0, v[10:11]
	v_lshl_add_u64 v[12:13], s[48:49], 0, v[12:13]
	v_lshl_add_u64 v[18:19], s[48:49], 0, v[18:19]
	v_lshl_add_u64 v[20:21], s[48:49], 0, v[20:21]
	v_lshl_add_u64 v[30:31], s[48:49], 0, v[30:31]
	v_lshl_add_u64 v[26:27], s[48:49], 0, v[26:27]
	v_lshl_add_u64 v[6:7], v[4:5], 0, v[28:29]
	v_lshl_add_u64 v[10:11], v[10:11], 0, v[28:29]
	v_lshl_add_u64 v[14:15], v[12:13], 0, v[28:29]
	v_lshl_add_u64 v[18:19], v[18:19], 0, v[28:29]
	v_lshl_add_u64 v[22:23], v[20:21], 0, v[28:29]
	v_lshl_add_u64 v[30:31], v[30:31], 0, v[28:29]
	v_lshl_add_u64 v[32:33], v[26:27], 0, v[28:29]
	global_load_dwordx4 v[2:5], v[2:3], off nt
	s_nop 0
	global_load_dwordx4 v[6:9], v[6:7], off nt
	s_nop 0
	global_load_dwordx4 v[10:13], v[10:11], off nt
	s_nop 0
	global_load_dwordx4 v[14:17], v[14:15], off nt
	s_nop 0
	global_load_dwordx4 v[18:21], v[18:19], off nt
	s_nop 0
	global_load_dwordx4 v[22:25], v[22:23], off nt
	s_nop 0
	global_load_dwordx4 v[26:29], v[30:31], off nt
	s_nop 0
	global_load_dwordx4 v[30:33], v[32:33], off nt
	v_ashrrev_i32_e32 v36, 1, v34
	v_lshlrev_b32_e32 v34, 5, v34
	v_and_b32_e32 v37, 32, v34
	s_movk_i32 s36, 0x104
	v_mad_u64_u32 v[34:35], s[38:39], v35, s36, v[0:1]
	v_mad_u32_u24 v0, v37, s36, v36
	v_lshl_add_u32 v38, v34, 2, 0
	v_lshl_add_u32 v39, v0, 2, 0
	v_add_u32_e32 v34, s3, v36
	v_ashrrev_i32_e32 v35, 31, v34
	v_readlane_b32 s36, v250, 45
	v_readlane_b32 s37, v250, 46
	s_ashr_i32 s3, s2, 31
	s_waitcnt vmcnt(7)
	ds_write_b128 v38, v[2:5]
	s_waitcnt vmcnt(6)
	ds_write_b128 v38, v[6:9] offset:8320
	s_waitcnt vmcnt(5)
	ds_write_b128 v38, v[10:13] offset:16640
	s_waitcnt vmcnt(4)
	ds_write_b128 v38, v[14:17] offset:24960
	s_waitcnt vmcnt(3)
	ds_write_b128 v38, v[18:21] offset:33280
	s_waitcnt vmcnt(2)
	ds_write_b128 v38, v[22:25] offset:41600
	s_waitcnt vmcnt(1)
	ds_write_b128 v38, v[26:29] offset:49920
	s_waitcnt vmcnt(0)
	ds_write_b128 v38, v[30:33] offset:58240
	s_waitcnt lgkmcnt(0)
	s_barrier
	ds_read_b32 v0, v39
	ds_read_b32 v2, v39 offset:1040
	ds_read_b32 v3, v39 offset:2080
	ds_read_b32 v4, v39 offset:3120
	ds_read_b32 v5, v39 offset:4160
	ds_read_b32 v6, v39 offset:5200
	ds_read_b32 v7, v39 offset:6240
	ds_read_b32 v8, v39 offset:7280
	s_waitcnt lgkmcnt(4)
	v_cvt_pk_bf16_f32 v3, v3, v4
	v_cvt_pk_bf16_f32 v2, v0, v2
	s_waitcnt lgkmcnt(2)
	v_cvt_pk_bf16_f32 v4, v5, v6
	v_lshlrev_b32_e32 v0, 1, v37
	s_waitcnt lgkmcnt(0)
	v_cvt_pk_bf16_f32 v5, v7, v8
	v_lshlrev_b64 v[6:7], 11, v[34:35]
	v_lshl_add_u64 v[6:7], s[36:37], 0, v[6:7]
	v_lshl_add_u64 v[6:7], s[2:3], 1, v[6:7]
	v_lshl_add_u64 v[6:7], v[6:7], 0, v[0:1]
	ds_read_b32 v0, v39 offset:8320
	ds_read_b32 v8, v39 offset:9360
	ds_read_b32 v9, v39 offset:10400
	ds_read_b32 v10, v39 offset:11440
	ds_read_b32 v11, v39 offset:12480
	ds_read_b32 v12, v39 offset:13520
	ds_read_b32 v13, v39 offset:14560
	ds_read_b32 v14, v39 offset:15600
	global_store_dwordx4 v[6:7], v[2:5], off
	s_waitcnt lgkmcnt(6)
	s_nop 0
	v_cvt_pk_bf16_f32 v2, v0, v8
	s_waitcnt lgkmcnt(4)
	v_cvt_pk_bf16_f32 v3, v9, v10
	s_waitcnt lgkmcnt(2)
	v_cvt_pk_bf16_f32 v4, v11, v12
	s_waitcnt lgkmcnt(0)
	v_cvt_pk_bf16_f32 v5, v13, v14
	ds_read_b32 v0, v39 offset:16640
	ds_read_b32 v8, v39 offset:17680
	ds_read_b32 v9, v39 offset:18720
	ds_read_b32 v10, v39 offset:19760
	ds_read_b32 v11, v39 offset:20800
	ds_read_b32 v12, v39 offset:21840
	ds_read_b32 v13, v39 offset:22880
	ds_read_b32 v14, v39 offset:23920
	global_store_dwordx4 v[6:7], v[2:5], off offset:16
	s_waitcnt lgkmcnt(6)
	s_nop 0
	v_cvt_pk_bf16_f32 v2, v0, v8
	s_waitcnt lgkmcnt(4)
	v_cvt_pk_bf16_f32 v3, v9, v10
	s_waitcnt lgkmcnt(2)
	v_cvt_pk_bf16_f32 v4, v11, v12
	s_waitcnt lgkmcnt(0)
	v_cvt_pk_bf16_f32 v5, v13, v14
	ds_read_b32 v0, v39 offset:24960
	ds_read_b32 v8, v39 offset:26000
	ds_read_b32 v9, v39 offset:27040
	ds_read_b32 v10, v39 offset:28080
	ds_read_b32 v11, v39 offset:29120
	ds_read_b32 v12, v39 offset:30160
	ds_read_b32 v13, v39 offset:31200
	ds_read_b32 v14, v39 offset:32240
	global_store_dwordx4 v[6:7], v[2:5], off offset:32
	s_waitcnt lgkmcnt(6)
	s_nop 0
	v_cvt_pk_bf16_f32 v2, v0, v8
	s_waitcnt lgkmcnt(4)
	v_cvt_pk_bf16_f32 v3, v9, v10
	s_waitcnt lgkmcnt(2)
	v_cvt_pk_bf16_f32 v4, v11, v12
	s_waitcnt lgkmcnt(0)
	v_cvt_pk_bf16_f32 v5, v13, v14
	global_store_dwordx4 v[6:7], v[2:5], off offset:48
	s_barrier

; DI void conv_tile(const ConvJob& J, int t, lptr lds) {
;     ...
;     for (int it = 0; it < 8; ++it) { const int kr = it * 8 + (tid >> 6), nc = (tid & 63) * 4;
;         int scol = n0s + nc;
;         if (n0d >= J.rlo && n0d < J.rhi) { const int d = n0d + nc - J.rlo, jj = d & 63, chunk = jj >> 3; scol = J.rlo + (n0s - n0d) + (d & ~63) + ((jj & 4) ? 32 + 4 * chunk : 4 * chunk); }
;         const f32x4 v = *(const f32x4*)(J.W + (size_t)(k0 + kr) * J.ldn + scol);
;         const float rsc = J.rs ? J.rs[k0 + kr] : 1.f;
;         lst<f32x4>(lds, (kr * 260 + nc) * 4, v * rsc); }
.LBB0_140:
	v_ashrrev_i32_e32 v11, 6, v8
	s_lshl_b32 s57, s57, 10
	v_subrev_u32_e32 v5, s57, v11
	v_add_u32_e32 v10, s55, v5
	v_mad_i64_i32 v[6:7], s[58:59], s11, v10, 0
	v_lshl_add_u64 v[6:7], v[6:7], 2, s[20:21]
	v_ashrrev_i32_e32 v5, 31, v4
	v_lshl_add_u64 v[4:5], v[4:5], 2, v[6:7]
	global_load_dwordx4 v[96:99], v[4:5], off nt
	s_movk_i32 s36, 0x104
	v_mad_u64_u32 v[4:5], s[58:59], v11, s36, v[0:1]
	s_and_b64 vcc, exec, s[38:39]
	v_lshl_add_u32 v5, v4, 2, 0
	v_mov_b32_e32 v6, v2
	v_mov_b32_e32 v124, v5
	s_cbranch_vccnz .LBB0_142
	v_lshrrev_b32_e32 v6, 1, v3
	v_subrev_u32_e32 v5, s15, v9
	v_and_b32_e32 v6, 28, v6
	v_lshlrev_b32_e32 v7, 3, v0
	s_or_b32 s58, s3, s15
	v_and_b32_e32 v5, 0xffffffc0, v5
	v_and_b32_e32 v7, 32, v7
	v_add_u32_e32 v6, s58, v6
	v_add3_u32 v6, v6, v7, v5
.LBB0_142:
	v_add_u32_e32 v5, 8, v10
	v_mad_i64_i32 v[12:13], s[58:59], s11, v5, 0
	v_lshl_add_u64 v[12:13], v[12:13], 2, s[20:21]
	v_ashrrev_i32_e32 v7, 31, v6
	v_lshl_add_u64 v[6:7], v[6:7], 2, v[12:13]
	global_load_dwordx4 v[100:103], v[6:7], off nt
	v_add_u32_e32 v6, 0x820, v4
	v_lshl_add_u32 v4, v6, 2, 0
	s_and_b64 vcc, exec, s[38:39]
	v_mov_b32_e32 v125, v4
	v_mov_b32_e32 v4, v2
	s_cbranch_vccnz .LBB0_144
	v_lshrrev_b32_e32 v5, 1, v3
	v_subrev_u32_e32 v4, s15, v9
	v_and_b32_e32 v5, 28, v5
	v_lshlrev_b32_e32 v7, 3, v0
	s_or_b32 s58, s3, s15
	v_and_b32_e32 v4, 0xffffffc0, v4
	v_and_b32_e32 v7, 32, v7
	v_add_u32_e32 v5, s58, v5
	v_add3_u32 v4, v5, v7, v4
.LBB0_144:
	v_add_u32_e32 v5, 16, v10
	v_mad_i64_i32 v[12:13], s[58:59], s11, v5, 0
	v_lshl_add_u64 v[12:13], v[12:13], 2, s[20:21]
	v_ashrrev_i32_e32 v5, 31, v4
	v_lshl_add_u64 v[4:5], v[4:5], 2, v[12:13]
	global_load_dwordx4 v[104:107], v[4:5], off nt
	v_add_u32_e32 v6, 0x820, v6
	v_lshl_add_u32 v4, v6, 2, 0
	s_and_b64 vcc, exec, s[38:39]
	v_mov_b32_e32 v126, v4
	v_mov_b32_e32 v4, v2
	s_cbranch_vccnz .LBB0_146
	v_lshrrev_b32_e32 v5, 1, v3
	v_subrev_u32_e32 v4, s15, v9
	v_and_b32_e32 v5, 28, v5
	v_lshlrev_b32_e32 v7, 3, v0
	s_or_b32 s58, s3, s15
	v_and_b32_e32 v4, 0xffffffc0, v4
	v_and_b32_e32 v7, 32, v7
	v_add_u32_e32 v5, s58, v5
	v_add3_u32 v4, v5, v7, v4
.LBB0_146:
	v_add_u32_e32 v5, 24, v10
	v_mad_i64_i32 v[12:13], s[58:59], s11, v5, 0
	v_lshl_add_u64 v[12:13], v[12:13], 2, s[20:21]
	v_ashrrev_i32_e32 v5, 31, v4
	v_lshl_add_u64 v[4:5], v[4:5], 2, v[12:13]
	global_load_dwordx4 v[108:111], v[4:5], off nt
	v_add_u32_e32 v6, 0x820, v6
	v_lshl_add_u32 v4, v6, 2, 0
	s_and_b64 vcc, exec, s[38:39]
	v_mov_b32_e32 v127, v4
	v_mov_b32_e32 v4, v2
	s_cbranch_vccnz .LBB0_148
	v_lshrrev_b32_e32 v5, 1, v3
	v_subrev_u32_e32 v4, s15, v9
	v_and_b32_e32 v5, 28, v5
	v_lshlrev_b32_e32 v7, 3, v0
	s_or_b32 s58, s3, s15
	v_and_b32_e32 v4, 0xffffffc0, v4
	v_and_b32_e32 v7, 32, v7
	v_add_u32_e32 v5, s58, v5
	v_add3_u32 v4, v5, v7, v4
.LBB0_148:
	v_add_u32_e32 v5, 32, v10
	v_mad_i64_i32 v[12:13], s[58:59], s11, v5, 0
	v_lshl_add_u64 v[12:13], v[12:13], 2, s[20:21]
	v_ashrrev_i32_e32 v5, 31, v4
	v_lshl_add_u64 v[4:5], v[4:5], 2, v[12:13]
	global_load_dwordx4 v[112:115], v[4:5], off nt
	v_add_u32_e32 v6, 0x820, v6
	v_lshl_add_u32 v4, v6, 2, 0
	s_and_b64 vcc, exec, s[38:39]
	v_mov_b32_e32 v128, v4
	v_mov_b32_e32 v4, v2
	s_cbranch_vccnz .LBB0_150
	v_lshrrev_b32_e32 v5, 1, v3
	v_subrev_u32_e32 v4, s15, v9
	v_and_b32_e32 v5, 28, v5
	v_lshlrev_b32_e32 v7, 3, v0
	s_or_b32 s58, s3, s15
	v_and_b32_e32 v4, 0xffffffc0, v4
	v_and_b32_e32 v7, 32, v7
	v_add_u32_e32 v5, s58, v5
	v_add3_u32 v4, v5, v7, v4
.LBB0_150:
	v_add_u32_e32 v5, 40, v10
	v_mad_i64_i32 v[12:13], s[58:59], s11, v5, 0
	v_lshl_add_u64 v[12:13], v[12:13], 2, s[20:21]
	v_ashrrev_i32_e32 v5, 31, v4
	v_lshl_add_u64 v[4:5], v[4:5], 2, v[12:13]
	global_load_dwordx4 v[116:119], v[4:5], off nt
	v_add_u32_e32 v6, 0x820, v6
	v_lshl_add_u32 v4, v6, 2, 0
	s_and_b64 vcc, exec, s[38:39]
	v_mov_b32_e32 v129, v4
	v_mov_b32_e32 v4, v2
	s_cbranch_vccnz .LBB0_152
	v_lshrrev_b32_e32 v5, 1, v3
	v_subrev_u32_e32 v4, s15, v9
	v_and_b32_e32 v5, 28, v5
	v_lshlrev_b32_e32 v7, 3, v0
	s_or_b32 s58, s3, s15
	v_and_b32_e32 v4, 0xffffffc0, v4
	v_and_b32_e32 v7, 32, v7
	v_add_u32_e32 v5, s58, v5
	v_add3_u32 v4, v5, v7, v4
.LBB0_152:
	v_add_u32_e32 v5, 48, v10
	v_mad_i64_i32 v[12:13], s[58:59], s11, v5, 0
	v_lshl_add_u64 v[12:13], v[12:13], 2, s[20:21]
	v_ashrrev_i32_e32 v5, 31, v4
	v_lshl_add_u64 v[4:5], v[4:5], 2, v[12:13]
	global_load_dwordx4 v[120:123], v[4:5], off nt
	v_add_u32_e32 v4, 0x820, v6
	v_lshl_add_u32 v4, v4, 2, 0
	s_and_b64 vcc, exec, s[38:39]
	v_mov_b32_e32 v130, v4
	s_cbranch_vccnz .LBB0_101
	v_lshrrev_b32_e32 v3, 1, v3
	v_subrev_u32_e32 v2, s15, v9
	v_and_b32_e32 v3, 28, v3
	v_lshlrev_b32_e32 v0, 3, v0
	s_or_b32 s3, s3, s15
	v_and_b32_e32 v2, 0xffffffc0, v2
	v_and_b32_e32 v0, 32, v0
	v_add_u32_e32 v3, s3, v3
	v_add3_u32 v2, v3, v0, v2
	s_branch .LBB0_101

; DI unsigned pk2(float lo, float hi) { f32x2_t v = {lo, hi}; bf16x2_t b = __builtin_convertvector(v, bf16x2_t); return __builtin_bit_cast(unsigned, b); }
; DI int tid_() { int t = threadIdx.x; asm volatile("" : "+v"(t)); return t; }
; DI int bid_() { return (int)blockIdx.x; }
; __global__ void __launch_bounds__(512) mega(Params p) {
;     ...
;             for (size_t i = (size_t)bid_() * 512 + tid_(); i < (size_t)MTOK * 256 / 4; i += (size_t)gridDim.x * 512) { const f32x4 v = *(const f32x4*)(ps + i * 4); u32x2 w; w.x = pk2(v[0], v[1]); w.y = pk2(v[2], v[3]); *(u32x2*)(PB + i * 4) = w; } }
.LBB0_159:
	global_load_dwordx4 v[8:11], v[4:5], off nt
	v_lshl_add_u64 v[2:3], v[2:3], 0, s[14:15]
	s_mov_b64 s[12:13], 0x1fffff
	v_cmp_lt_u64_e32 vcc, s[12:13], v[2:3]
	v_lshl_add_u64 v[4:5], v[4:5], 0, s[16:17]
	s_or_b64 s[2:3], vcc, s[2:3]
	s_waitcnt vmcnt(0)
	v_cvt_pk_bf16_f32 v8, v8, v9
	v_cvt_pk_bf16_f32 v9, v10, v11
	global_store_dwordx2 v[6:7], v[8:9], off
	v_lshl_add_u64 v[6:7], v[6:7], 0, s[18:19]
	s_andn2_b64 exec, exec, s[2:3]
	s_cbranch_execnz .LBB0_159
